# bundle: relaxed first-iteration K-loop waits (P1/P4/P11, early row-scale loads) + loop-back SALU hoisted above the barrier in all K-loops
# baseline (speedup 1.0000x reference)
; #define PG8_STAGE(bufoff, gbase, voff) do { _Pragma("unroll") for (int _i = 0; _i < 2; ++_i) \
;         __builtin_amdgcn_global_load_lds((const unsigned*)((const char*)(gbase) + (voff)[_i]), (PG8_LAS unsigned*)(lds + (bufoff) + ldsw + _i * 8192), 16, 0, 0); } while (0)
; #define PG8_LDA(dst, b, h) do { _Pragma("unroll") for (int m = 0; m < 4; ++m) _Pragma("unroll") for (int k = 0; k < 2; ++k) dst[m][k] = *(const PG8_LAS bf16x8*)(lds + PG8_SA(b, h) + aoff + m * 2048 + k * 1024); } while (0)
; #define PG8_LDB(dst, b, h) do { _Pragma("unroll") for (int n = 0; n < 2; ++n) _Pragma("unroll") for (int k = 0; k < 2; ++k) dst[n][k] = *(const PG8_LAS bf16x8*)(lds + PG8_SB(b, h) + boff + n * 2048 + k * 1024); } while (0)
; #define PG8_MMA(ai, bj, At, Bt) do { __builtin_amdgcn_s_setprio(1); _Pragma("unroll") for (int m = 0; m < 4; ++m) _Pragma("unroll") for (int n = 0; n < 2; ++n) _Pragma("unroll") for (int k = 0; k < 2; ++k) \
;         acc[ai][bj][m][n] = __builtin_amdgcn_mfma_f32_16x16x32_bf16(Bt[n][k], At[m][k], acc[ai][bj][m][n], 0, 0, 0); __builtin_amdgcn_s_setprio(0); } while (0)
; #define PG8_WAIT_V(n) asm volatile("s_waitcnt vmcnt(" #n ")" ::: "memory")
; #define PG8_WAIT_L(n) asm volatile("s_waitcnt lgkmcnt(" #n ")" ::: "memory")
; #define PG8_BAR __builtin_amdgcn_s_barrier()
; #define PG8_SCHED __builtin_amdgcn_sched_barrier(0)
; template <class Epi, class Sched, bool ALIGN_EPI = false, bool SP2 = false>
; __device__ __forceinline__ void gemm_phase(PG8_LAS unsigned char* lds, const Gemm g, const Sched& S, const Epi& E) {
;     ...
;             PG8_WAIT_V(8); PG8_WAIT_L(0); PG8_BAR; PG8_MMA(1, 0, At, B0); PG8_MMA(1, 1, At, B1); PG8_BAR; PG8_SCHED;
;             PG8_LDB(B0, 1, 0); PG8_LDB(B1, 1, 1); PG8_SCHED; PG8_LDA(At, 1, 0); PG8_STAGE(PG8_SA(0, 1), a2 + hstep, voffA);
;             PG8_WAIT_V(8); PG8_WAIT_L(0); PG8_BAR; PG8_MMA(0, 0, At, B0); PG8_MMA(0, 1, At, B1); PG8_BAR; PG8_SCHED;
.Lrw0_b1:
	s_waitcnt lgkmcnt(0)
	s_barrier
	s_setprio 1
	s_waitcnt lgkmcnt(0)
	v_mfma_f32_16x16x32_bf16 v[60:63], v[144:147], v[182:185], v[60:63]
	v_mfma_f32_16x16x32_bf16 v[56:59], v[158:161], v[182:185], v[56:59]
	v_mfma_f32_16x16x32_bf16 v[44:47], v[144:147], v[190:193], v[44:47]
	v_mfma_f32_16x16x32_bf16 v[40:43], v[158:161], v[190:193], v[40:43]
	v_mfma_f32_16x16x32_bf16 v[28:31], v[144:147], v[202:205], v[28:31]
	v_mfma_f32_16x16x32_bf16 v[24:27], v[158:161], v[202:205], v[24:27]
	v_mfma_f32_16x16x32_bf16 v[12:15], v[144:147], v[210:213], v[12:15]
	v_mfma_f32_16x16x32_bf16 v[8:11], v[158:161], v[210:213], v[8:11]
	v_mfma_f32_16x16x32_bf16 v[60:63], v[154:157], v[186:189], v[60:63]
	v_mfma_f32_16x16x32_bf16 v[56:59], v[162:165], v[186:189], v[56:59]
	v_mfma_f32_16x16x32_bf16 v[44:47], v[154:157], v[198:201], v[44:47]
	v_mfma_f32_16x16x32_bf16 v[40:43], v[162:165], v[198:201], v[40:43]
	v_mfma_f32_16x16x32_bf16 v[28:31], v[154:157], v[206:209], v[28:31]
	v_mfma_f32_16x16x32_bf16 v[24:27], v[162:165], v[206:209], v[24:27]
	v_mfma_f32_16x16x32_bf16 v[12:15], v[154:157], v[214:217], v[12:15]
	v_mfma_f32_16x16x32_bf16 v[8:11], v[162:165], v[214:217], v[8:11]
	s_setprio 0
	s_setprio 1
	v_mfma_f32_16x16x32_bf16 v[52:55], v[166:169], v[182:185], v[52:55]
	v_mfma_f32_16x16x32_bf16 v[48:51], v[174:177], v[182:185], v[48:51]
	v_mfma_f32_16x16x32_bf16 v[36:39], v[166:169], v[190:193], v[36:39]
	v_mfma_f32_16x16x32_bf16 v[32:35], v[174:177], v[190:193], v[32:35]
	v_mfma_f32_16x16x32_bf16 v[20:23], v[166:169], v[202:205], v[20:23]
	v_mfma_f32_16x16x32_bf16 v[16:19], v[174:177], v[202:205], v[16:19]
	v_mfma_f32_16x16x32_bf16 v[4:7], v[166:169], v[210:213], v[4:7]
	v_mfma_f32_16x16x32_bf16 v[0:3], v[174:177], v[210:213], v[0:3]
	v_mfma_f32_16x16x32_bf16 v[52:55], v[170:173], v[186:189], v[52:55]
	v_mfma_f32_16x16x32_bf16 v[48:51], v[178:181], v[186:189], v[48:51]
	v_mfma_f32_16x16x32_bf16 v[36:39], v[170:173], v[198:201], v[36:39]
	v_mfma_f32_16x16x32_bf16 v[32:35], v[178:181], v[198:201], v[32:35]
	v_mfma_f32_16x16x32_bf16 v[20:23], v[170:173], v[206:209], v[20:23]
	v_mfma_f32_16x16x32_bf16 v[16:19], v[178:181], v[206:209], v[16:19]
	v_mfma_f32_16x16x32_bf16 v[4:7], v[170:173], v[214:217], v[4:7]
	v_mfma_f32_16x16x32_bf16 v[0:3], v[178:181], v[214:217], v[0:3]
	s_setprio 0
	s_barrier
	s_add_i32 s51, 0, 0x18000
	s_add_i32 s52, 0, 0x1c000
	v_add_u32_e32 v162, s51, v149
	v_add_u32_e32 v178, s52, v149
	ds_read_b128 v[144:147], v162
	ds_read_b128 v[154:157], v162 offset:1024
	ds_read_b128 v[158:161], v162 offset:2048
	ds_read_b128 v[162:165], v162 offset:3072
	ds_read_b128 v[166:169], v178
	ds_read_b128 v[170:173], v178 offset:1024
	ds_read_b128 v[174:177], v178 offset:2048
	ds_read_b128 v[178:181], v178 offset:3072
	s_add_u32 s28, s28, 0x40000
	s_addc_u32 s29, s29, 0
	s_mov_b32 m0, s35
	v_lshl_add_u64 v[224:225], s[28:29], 0, v[128:129]
	ds_read_b128 v[182:185], v153 offset:32768
	ds_read_b128 v[186:189], v153 offset:33792
	ds_read_b128 v[190:193], v153 offset:34816
	ds_read_b128 v[198:201], v153 offset:35840
	ds_read_b128 v[202:205], v153 offset:36864
	ds_read_b128 v[206:209], v153 offset:37888
	ds_read_b128 v[210:213], v153 offset:38912
	ds_read_b128 v[214:217], v153 offset:39936
	global_load_lds_dwordx4 v[224:225], off
	v_lshl_add_u64 v[224:225], s[28:29], 0, v[132:133]
	s_mov_b32 m0, s36
	s_nop 0
	global_load_lds_dwordx4 v[224:225], off
	s_waitcnt vmcnt(8)
	s_waitcnt lgkmcnt(0)
	s_barrier
	s_setprio 1
	s_waitcnt lgkmcnt(0)
	v_mfma_f32_16x16x32_bf16 v[124:127], v[144:147], v[182:185], v[124:127]
	v_mfma_f32_16x16x32_bf16 v[120:123], v[158:161], v[182:185], v[120:123]
	v_mfma_f32_16x16x32_bf16 v[108:111], v[144:147], v[190:193], v[108:111]
	v_mfma_f32_16x16x32_bf16 v[104:107], v[158:161], v[190:193], v[104:107]
	v_mfma_f32_16x16x32_bf16 v[92:95], v[144:147], v[202:205], v[92:95]
	v_mfma_f32_16x16x32_bf16 v[88:91], v[158:161], v[202:205], v[88:91]
	v_mfma_f32_16x16x32_bf16 v[76:79], v[144:147], v[210:213], v[76:79]
	v_mfma_f32_16x16x32_bf16 v[72:75], v[158:161], v[210:213], v[72:75]
	v_mfma_f32_16x16x32_bf16 v[124:127], v[154:157], v[186:189], v[124:127]
	v_mfma_f32_16x16x32_bf16 v[120:123], v[162:165], v[186:189], v[120:123]
	v_mfma_f32_16x16x32_bf16 v[108:111], v[154:157], v[198:201], v[108:111]
	v_mfma_f32_16x16x32_bf16 v[104:107], v[162:165], v[198:201], v[104:107]
	v_mfma_f32_16x16x32_bf16 v[92:95], v[154:157], v[206:209], v[92:95]
	v_mfma_f32_16x16x32_bf16 v[88:91], v[162:165], v[206:209], v[88:91]
	v_mfma_f32_16x16x32_bf16 v[76:79], v[154:157], v[214:217], v[76:79]
	v_mfma_f32_16x16x32_bf16 v[72:75], v[162:165], v[214:217], v[72:75]
	s_setprio 0
	s_setprio 1
	v_mfma_f32_16x16x32_bf16 v[116:119], v[166:169], v[182:185], v[116:119]
	v_mfma_f32_16x16x32_bf16 v[112:115], v[174:177], v[182:185], v[112:115]
	v_mfma_f32_16x16x32_bf16 v[100:103], v[166:169], v[190:193], v[100:103]
	v_mfma_f32_16x16x32_bf16 v[96:99], v[174:177], v[190:193], v[96:99]
	v_mfma_f32_16x16x32_bf16 v[84:87], v[166:169], v[202:205], v[84:87]
	v_mfma_f32_16x16x32_bf16 v[80:83], v[174:177], v[202:205], v[80:83]
	v_mfma_f32_16x16x32_bf16 v[68:71], v[166:169], v[210:213], v[68:71]
	v_mfma_f32_16x16x32_bf16 v[64:67], v[174:177], v[210:213], v[64:67]
	v_mfma_f32_16x16x32_bf16 v[116:119], v[170:173], v[186:189], v[116:119]
	v_mfma_f32_16x16x32_bf16 v[112:115], v[178:181], v[186:189], v[112:115]
	v_mfma_f32_16x16x32_bf16 v[100:103], v[170:173], v[198:201], v[100:103]
	v_mfma_f32_16x16x32_bf16 v[96:99], v[178:181], v[198:201], v[96:99]
	v_mfma_f32_16x16x32_bf16 v[84:87], v[170:173], v[206:209], v[84:87]
	v_mfma_f32_16x16x32_bf16 v[80:83], v[178:181], v[206:209], v[80:83]
	v_mfma_f32_16x16x32_bf16 v[68:71], v[170:173], v[214:217], v[68:71]
	v_mfma_f32_16x16x32_bf16 v[64:67], v[178:181], v[214:217], v[64:67]
	s_setprio 0
	s_barrier
; #define PG8_STAGE(bufoff, gbase, voff) do { _Pragma("unroll") for (int _i = 0; _i < 2; ++_i) \
;         __builtin_amdgcn_global_load_lds((const unsigned*)((const char*)(gbase) + (voff)[_i]), (PG8_LAS unsigned*)(lds + (bufoff) + ldsw + _i * 8192), 16, 0, 0); } while (0)
; #define PG8_LDA(dst, b, h) do { _Pragma("unroll") for (int m = 0; m < 4; ++m) _Pragma("unroll") for (int k = 0; k < 2; ++k) dst[m][k] = *(const PG8_LAS bf16x8*)(lds + PG8_SA(b, h) + aoff + m * 2048 + k * 1024); } while (0)
; #define PG8_MMA(ai, bj, At, Bt) do { __builtin_amdgcn_s_setprio(1); _Pragma("unroll") for (int m = 0; m < 4; ++m) _Pragma("unroll") for (int n = 0; n < 2; ++n) _Pragma("unroll") for (int k = 0; k < 2; ++k) \
;         acc[ai][bj][m][n] = __builtin_amdgcn_mfma_f32_16x16x32_bf16(Bt[n][k], At[m][k], acc[ai][bj][m][n], 0, 0, 0); __builtin_amdgcn_s_setprio(0); } while (0)
; #define PG8_WAIT_V(n) asm volatile("s_waitcnt vmcnt(" #n ")" ::: "memory")
; #define PG8_WAIT_L(n) asm volatile("s_waitcnt lgkmcnt(" #n ")" ::: "memory")
; #define PG8_BAR __builtin_amdgcn_s_barrier()
; #define PG8_SCHED __builtin_amdgcn_sched_barrier(0)
; template <class Epi, class Sched, bool ALIGN_EPI = false, bool SP2 = false>
; __device__ __forceinline__ void gemm_phase(PG8_LAS unsigned char* lds, const Gemm g, const Sched& S, const Epi& E) {
;     ...
;             PG8_LDA(At, 1, 1); PG8_STAGE(PG8_SB(1, 0), b3, voffB); PG8_STAGE(PG8_SB(1, 1), b3 + hstep, voffB); PG8_STAGE(PG8_SA(1, 0), a3, voffA);
;             PG8_WAIT_V(8); PG8_WAIT_L(0); PG8_BAR; PG8_MMA(1, 0, At, B0); PG8_MMA(1, 1, At, B1); PG8_BAR; PG8_SCHED;
	s_add_i32 s28, s51, s30
	v_lshl_add_u64 v[194:195], v[194:195], 0, s[10:11]
	s_mov_b32 m0, s28
	ds_read_b128 v[182:185], v153 offset:49152
	ds_read_b128 v[186:189], v153 offset:50176
	ds_read_b128 v[190:193], v153 offset:51200
	ds_read_b128 v[198:201], v153 offset:52224
	ds_read_b128 v[202:205], v153 offset:53248
	ds_read_b128 v[206:209], v153 offset:54272
	ds_read_b128 v[210:213], v153 offset:55296
	ds_read_b128 v[214:217], v153 offset:56320
	global_load_lds_dwordx4 v[194:195], off
	s_add_i32 m0, s28, 0x2000
	s_add_u32 s26, s26, 0x40080
	v_lshl_add_u64 v[194:195], v[218:219], 0, s[10:11]
	s_addc_u32 s27, s27, 0
	s_add_i32 s28, s52, s30
	global_load_lds_dwordx4 v[194:195], off
	v_lshl_add_u64 v[194:195], s[26:27], 0, v[130:131]
	s_mov_b32 m0, s28
	s_nop 0
	global_load_lds_dwordx4 v[194:195], off
	v_lshl_add_u64 v[194:195], s[26:27], 0, v[134:135]
	s_add_i32 m0, s28, 0x2000
	s_nop 0
	global_load_lds_dwordx4 v[194:195], off
	v_lshl_add_u64 v[194:195], v[220:221], 0, s[10:11]
	s_mov_b32 m0, s39
	s_nop 0
	global_load_lds_dwordx4 v[194:195], off
	v_lshl_add_u64 v[194:195], v[222:223], 0, s[10:11]
	s_mov_b32 m0, s40
	s_nop 0
	global_load_lds_dwordx4 v[194:195], off
	s_waitcnt vmcnt(8)
	s_waitcnt lgkmcnt(0)
	s_barrier
	s_setprio 1
	s_waitcnt lgkmcnt(0)
	v_mfma_f32_16x16x32_bf16 v[60:63], v[144:147], v[182:185], v[60:63]
	v_mfma_f32_16x16x32_bf16 v[56:59], v[158:161], v[182:185], v[56:59]
	v_mfma_f32_16x16x32_bf16 v[44:47], v[144:147], v[190:193], v[44:47]
	v_mfma_f32_16x16x32_bf16 v[40:43], v[158:161], v[190:193], v[40:43]
	v_mfma_f32_16x16x32_bf16 v[28:31], v[144:147], v[202:205], v[28:31]
	v_mfma_f32_16x16x32_bf16 v[24:27], v[158:161], v[202:205], v[24:27]
	v_mfma_f32_16x16x32_bf16 v[12:15], v[144:147], v[210:213], v[12:15]
	v_mfma_f32_16x16x32_bf16 v[8:11], v[158:161], v[210:213], v[8:11]
	v_mfma_f32_16x16x32_bf16 v[60:63], v[154:157], v[186:189], v[60:63]
	v_mfma_f32_16x16x32_bf16 v[56:59], v[162:165], v[186:189], v[56:59]
	v_mfma_f32_16x16x32_bf16 v[44:47], v[154:157], v[198:201], v[44:47]
	v_mfma_f32_16x16x32_bf16 v[40:43], v[162:165], v[198:201], v[40:43]
	v_mfma_f32_16x16x32_bf16 v[28:31], v[154:157], v[206:209], v[28:31]
	v_mfma_f32_16x16x32_bf16 v[24:27], v[162:165], v[206:209], v[24:27]
	v_mfma_f32_16x16x32_bf16 v[12:15], v[154:157], v[214:217], v[12:15]
	v_mfma_f32_16x16x32_bf16 v[8:11], v[162:165], v[214:217], v[8:11]
	s_setprio 0
	s_setprio 1
	v_mfma_f32_16x16x32_bf16 v[52:55], v[166:169], v[182:185], v[52:55]
	v_mfma_f32_16x16x32_bf16 v[48:51], v[174:177], v[182:185], v[48:51]
	v_mfma_f32_16x16x32_bf16 v[36:39], v[166:169], v[190:193], v[36:39]
	v_mfma_f32_16x16x32_bf16 v[32:35], v[174:177], v[190:193], v[32:35]
	v_mfma_f32_16x16x32_bf16 v[20:23], v[166:169], v[202:205], v[20:23]
	v_mfma_f32_16x16x32_bf16 v[16:19], v[174:177], v[202:205], v[16:19]
	v_mfma_f32_16x16x32_bf16 v[4:7], v[166:169], v[210:213], v[4:7]
	v_mfma_f32_16x16x32_bf16 v[0:3], v[174:177], v[210:213], v[0:3]
	v_mfma_f32_16x16x32_bf16 v[52:55], v[170:173], v[186:189], v[52:55]
	v_mfma_f32_16x16x32_bf16 v[48:51], v[178:181], v[186:189], v[48:51]
	v_mfma_f32_16x16x32_bf16 v[36:39], v[170:173], v[198:201], v[36:39]
	v_mfma_f32_16x16x32_bf16 v[32:35], v[178:181], v[198:201], v[32:35]
	v_mfma_f32_16x16x32_bf16 v[20:23], v[170:173], v[206:209], v[20:23]
	v_mfma_f32_16x16x32_bf16 v[16:19], v[178:181], v[206:209], v[16:19]
	v_mfma_f32_16x16x32_bf16 v[4:7], v[170:173], v[214:217], v[4:7]
	v_mfma_f32_16x16x32_bf16 v[0:3], v[178:181], v[214:217], v[0:3]
	s_setprio 0
	s_add_i32 s50, s50, 2
	s_add_u32 s24, s24, 0x100
	s_addc_u32 s25, s25, 0
	s_add_u32 s48, s48, 0x100
	s_addc_u32 s49, s49, 0
	s_cmp_gt_u32 s50, 13
	s_barrier
	s_cbranch_scc0 .LBB0_293
	s_branch .Lrw0_x

; #define PG8_STAGE(bufoff, gbase, voff) do { _Pragma("unroll") for (int _i = 0; _i < 2; ++_i) \
;         __builtin_amdgcn_global_load_lds((const unsigned*)((const char*)(gbase) + (voff)[_i]), (PG8_LAS unsigned*)(lds + (bufoff) + ldsw + _i * 8192), 16, 0, 0); } while (0)
; #define PG8_LDA(dst, b, h) do { _Pragma("unroll") for (int m = 0; m < 4; ++m) _Pragma("unroll") for (int k = 0; k < 2; ++k) dst[m][k] = *(const PG8_LAS bf16x8*)(lds + PG8_SA(b, h) + aoff + m * 2048 + k * 1024); } while (0)
; #define PG8_LDB(dst, b, h) do { _Pragma("unroll") for (int n = 0; n < 2; ++n) _Pragma("unroll") for (int k = 0; k < 2; ++k) dst[n][k] = *(const PG8_LAS bf16x8*)(lds + PG8_SB(b, h) + boff + n * 2048 + k * 1024); } while (0)
; #define PG8_MMA(ai, bj, At, Bt) do { __builtin_amdgcn_s_setprio(1); _Pragma("unroll") for (int m = 0; m < 4; ++m) _Pragma("unroll") for (int n = 0; n < 2; ++n) _Pragma("unroll") for (int k = 0; k < 2; ++k) \
;         acc[ai][bj][m][n] = __builtin_amdgcn_mfma_f32_16x16x32_bf16(Bt[n][k], At[m][k], acc[ai][bj][m][n], 0, 0, 0); __builtin_amdgcn_s_setprio(0); } while (0)
; #define PG8_WAIT_V(n) asm volatile("s_waitcnt vmcnt(" #n ")" ::: "memory")
; #define PG8_WAIT_L(n) asm volatile("s_waitcnt lgkmcnt(" #n ")" ::: "memory")
; #define PG8_BAR __builtin_amdgcn_s_barrier()
; #define PG8_SCHED __builtin_amdgcn_sched_barrier(0)
; template <class Epi, class Sched, bool ALIGN_EPI = false, bool SP2 = false>
; __device__ __forceinline__ void gemm_phase(PG8_LAS unsigned char* lds, const Gemm g, const Sched& S, const Epi& E) {
;     ...
;             PG8_WAIT_V(8); PG8_WAIT_L(0); PG8_BAR; PG8_MMA(1, 0, At, B0); PG8_MMA(1, 1, At, B1); PG8_BAR; PG8_SCHED;
;             PG8_LDB(B0, 1, 0); PG8_LDB(B1, 1, 1); PG8_SCHED; PG8_LDA(At, 1, 0); PG8_STAGE(PG8_SA(0, 1), a2 + hstep, voffA);
;             PG8_WAIT_V(8); PG8_WAIT_L(0); PG8_BAR; PG8_MMA(0, 0, At, B0); PG8_MMA(0, 1, At, B1); PG8_BAR; PG8_SCHED;
.Lrw1_b1:
	s_waitcnt lgkmcnt(0)
	s_barrier
	s_setprio 1
	s_waitcnt lgkmcnt(0)
	v_mfma_f32_16x16x32_bf16 v[92:95], v[144:147], v[186:189], v[92:95]
	v_mfma_f32_16x16x32_bf16 v[88:91], v[162:165], v[186:189], v[88:91]
	v_mfma_f32_16x16x32_bf16 v[84:87], v[144:147], v[198:201], v[84:87]
	v_mfma_f32_16x16x32_bf16 v[80:83], v[162:165], v[198:201], v[80:83]
	v_mfma_f32_16x16x32_bf16 v[76:79], v[144:147], v[206:209], v[76:79]
	v_mfma_f32_16x16x32_bf16 v[72:75], v[162:165], v[206:209], v[72:75]
	v_mfma_f32_16x16x32_bf16 v[68:71], v[144:147], v[214:217], v[68:71]
	v_mfma_f32_16x16x32_bf16 v[60:63], v[162:165], v[214:217], v[60:63]
	v_mfma_f32_16x16x32_bf16 v[92:95], v[148:151], v[190:193], v[92:95]
	v_mfma_f32_16x16x32_bf16 v[88:91], v[166:169], v[190:193], v[88:91]
	v_mfma_f32_16x16x32_bf16 v[84:87], v[148:151], v[202:205], v[84:87]
	v_mfma_f32_16x16x32_bf16 v[80:83], v[166:169], v[202:205], v[80:83]
	v_mfma_f32_16x16x32_bf16 v[76:79], v[148:151], v[210:213], v[76:79]
	v_mfma_f32_16x16x32_bf16 v[72:75], v[166:169], v[210:213], v[72:75]
	v_mfma_f32_16x16x32_bf16 v[68:71], v[148:151], v[218:221], v[68:71]
	v_mfma_f32_16x16x32_bf16 v[60:63], v[166:169], v[218:221], v[60:63]
	s_setprio 0
	s_setprio 1
	v_mfma_f32_16x16x32_bf16 v[28:31], v[170:173], v[186:189], v[28:31]
	v_mfma_f32_16x16x32_bf16 v[24:27], v[178:181], v[186:189], v[24:27]
	v_mfma_f32_16x16x32_bf16 v[20:23], v[170:173], v[198:201], v[20:23]
	v_mfma_f32_16x16x32_bf16 v[16:19], v[178:181], v[198:201], v[16:19]
	v_mfma_f32_16x16x32_bf16 v[12:15], v[170:173], v[206:209], v[12:15]
	v_mfma_f32_16x16x32_bf16 v[8:11], v[178:181], v[206:209], v[8:11]
	v_mfma_f32_16x16x32_bf16 v[4:7], v[170:173], v[214:217], v[4:7]
	v_mfma_f32_16x16x32_bf16 v[0:3], v[178:181], v[214:217], v[0:3]
	v_mfma_f32_16x16x32_bf16 v[28:31], v[174:177], v[190:193], v[28:31]
	v_mfma_f32_16x16x32_bf16 v[24:27], v[182:185], v[190:193], v[24:27]
	v_mfma_f32_16x16x32_bf16 v[20:23], v[174:177], v[202:205], v[20:23]
	v_mfma_f32_16x16x32_bf16 v[16:19], v[182:185], v[202:205], v[16:19]
	v_mfma_f32_16x16x32_bf16 v[12:15], v[174:177], v[210:213], v[12:15]
	v_mfma_f32_16x16x32_bf16 v[8:11], v[182:185], v[210:213], v[8:11]
	v_mfma_f32_16x16x32_bf16 v[4:7], v[174:177], v[218:221], v[4:7]
	v_mfma_f32_16x16x32_bf16 v[0:3], v[182:185], v[218:221], v[0:3]
	s_setprio 0
	s_barrier
	s_add_i32 s54, 0, 0x18000
	v_add_u32_e32 v152, s54, v155
	s_add_i32 s55, 0, 0x1c000
	ds_read_b128 v[144:147], v152
	ds_read_b128 v[148:151], v152 offset:1024
	ds_read_b128 v[162:165], v152 offset:2048
	ds_read_b128 v[166:169], v152 offset:3072
	v_add_u32_e32 v152, s55, v155
	ds_read_b128 v[170:173], v152
	ds_read_b128 v[174:177], v152 offset:1024
	ds_read_b128 v[178:181], v152 offset:2048
	ds_read_b128 v[182:185], v152 offset:3072
	s_add_u32 s36, s36, 0x40000
	s_addc_u32 s37, s37, 0
	s_mov_b32 m0, s39
	v_lshl_add_u64 v[228:229], s[36:37], 0, v[128:129]
	ds_read_b128 v[186:189], v159 offset:32768
	ds_read_b128 v[190:193], v159 offset:33792
	ds_read_b128 v[198:201], v159 offset:34816
	ds_read_b128 v[202:205], v159 offset:35840
	ds_read_b128 v[206:209], v159 offset:36864
	ds_read_b128 v[210:213], v159 offset:37888
	ds_read_b128 v[214:217], v159 offset:38912
	ds_read_b128 v[218:221], v159 offset:39936
	global_load_lds_dwordx4 v[228:229], off
	v_lshl_add_u64 v[228:229], s[36:37], 0, v[132:133]
	s_mov_b32 m0, s40
	s_nop 0
	global_load_lds_dwordx4 v[228:229], off
	s_waitcnt vmcnt(8)
	s_waitcnt lgkmcnt(0)
	s_barrier
	s_setprio 1
	s_waitcnt lgkmcnt(0)
	v_mfma_f32_16x16x32_bf16 v[124:127], v[144:147], v[186:189], v[124:127]
	v_mfma_f32_16x16x32_bf16 v[120:123], v[162:165], v[186:189], v[120:123]
	v_mfma_f32_16x16x32_bf16 v[116:119], v[144:147], v[198:201], v[116:119]
	v_mfma_f32_16x16x32_bf16 v[112:115], v[162:165], v[198:201], v[112:115]
	v_mfma_f32_16x16x32_bf16 v[108:111], v[144:147], v[206:209], v[108:111]
	v_mfma_f32_16x16x32_bf16 v[104:107], v[162:165], v[206:209], v[104:107]
	v_mfma_f32_16x16x32_bf16 v[100:103], v[144:147], v[214:217], v[100:103]
	v_mfma_f32_16x16x32_bf16 v[96:99], v[162:165], v[214:217], v[96:99]
	v_mfma_f32_16x16x32_bf16 v[124:127], v[148:151], v[190:193], v[124:127]
	v_mfma_f32_16x16x32_bf16 v[120:123], v[166:169], v[190:193], v[120:123]
	v_mfma_f32_16x16x32_bf16 v[116:119], v[148:151], v[202:205], v[116:119]
	v_mfma_f32_16x16x32_bf16 v[112:115], v[166:169], v[202:205], v[112:115]
	v_mfma_f32_16x16x32_bf16 v[108:111], v[148:151], v[210:213], v[108:111]
	v_mfma_f32_16x16x32_bf16 v[104:107], v[166:169], v[210:213], v[104:107]
	v_mfma_f32_16x16x32_bf16 v[100:103], v[148:151], v[218:221], v[100:103]
	v_mfma_f32_16x16x32_bf16 v[96:99], v[166:169], v[218:221], v[96:99]
	s_setprio 0
	s_setprio 1
	v_mfma_f32_16x16x32_bf16 v[64:67], v[170:173], v[186:189], v[64:67]
	v_mfma_f32_16x16x32_bf16 v[56:59], v[178:181], v[186:189], v[56:59]
	v_mfma_f32_16x16x32_bf16 v[52:55], v[170:173], v[198:201], v[52:55]
	v_mfma_f32_16x16x32_bf16 v[48:51], v[178:181], v[198:201], v[48:51]
	v_mfma_f32_16x16x32_bf16 v[44:47], v[170:173], v[206:209], v[44:47]
	v_mfma_f32_16x16x32_bf16 v[40:43], v[178:181], v[206:209], v[40:43]
	v_mfma_f32_16x16x32_bf16 v[36:39], v[170:173], v[214:217], v[36:39]
	v_mfma_f32_16x16x32_bf16 v[32:35], v[178:181], v[214:217], v[32:35]
	v_mfma_f32_16x16x32_bf16 v[64:67], v[174:177], v[190:193], v[64:67]
	v_mfma_f32_16x16x32_bf16 v[56:59], v[182:185], v[190:193], v[56:59]
	v_mfma_f32_16x16x32_bf16 v[52:55], v[174:177], v[202:205], v[52:55]
	v_mfma_f32_16x16x32_bf16 v[48:51], v[182:185], v[202:205], v[48:51]
	v_mfma_f32_16x16x32_bf16 v[44:47], v[174:177], v[210:213], v[44:47]
	v_mfma_f32_16x16x32_bf16 v[40:43], v[182:185], v[210:213], v[40:43]
	v_mfma_f32_16x16x32_bf16 v[36:39], v[174:177], v[218:221], v[36:39]
	v_mfma_f32_16x16x32_bf16 v[32:35], v[182:185], v[218:221], v[32:35]
	s_setprio 0
	s_barrier
; #define PG8_STAGE(bufoff, gbase, voff) do { _Pragma("unroll") for (int _i = 0; _i < 2; ++_i) \
;         __builtin_amdgcn_global_load_lds((const unsigned*)((const char*)(gbase) + (voff)[_i]), (PG8_LAS unsigned*)(lds + (bufoff) + ldsw + _i * 8192), 16, 0, 0); } while (0)
; #define PG8_LDA(dst, b, h) do { _Pragma("unroll") for (int m = 0; m < 4; ++m) _Pragma("unroll") for (int k = 0; k < 2; ++k) dst[m][k] = *(const PG8_LAS bf16x8*)(lds + PG8_SA(b, h) + aoff + m * 2048 + k * 1024); } while (0)
; #define PG8_MMA(ai, bj, At, Bt) do { __builtin_amdgcn_s_setprio(1); _Pragma("unroll") for (int m = 0; m < 4; ++m) _Pragma("unroll") for (int n = 0; n < 2; ++n) _Pragma("unroll") for (int k = 0; k < 2; ++k) \
;         acc[ai][bj][m][n] = __builtin_amdgcn_mfma_f32_16x16x32_bf16(Bt[n][k], At[m][k], acc[ai][bj][m][n], 0, 0, 0); __builtin_amdgcn_s_setprio(0); } while (0)
; #define PG8_WAIT_V(n) asm volatile("s_waitcnt vmcnt(" #n ")" ::: "memory")
; #define PG8_WAIT_L(n) asm volatile("s_waitcnt lgkmcnt(" #n ")" ::: "memory")
; #define PG8_BAR __builtin_amdgcn_s_barrier()
; #define PG8_SCHED __builtin_amdgcn_sched_barrier(0)
; template <class Epi, class Sched, bool ALIGN_EPI = false, bool SP2 = false>
; __device__ __forceinline__ void gemm_phase(PG8_LAS unsigned char* lds, const Gemm g, const Sched& S, const Epi& E) {
;     ...
;             PG8_LDA(At, 1, 1); PG8_STAGE(PG8_SB(1, 0), b3, voffB); PG8_STAGE(PG8_SB(1, 1), b3 + hstep, voffB); PG8_STAGE(PG8_SA(1, 0), a3, voffA);
;             PG8_WAIT_V(8); PG8_WAIT_L(0); PG8_BAR; PG8_MMA(1, 0, At, B0); PG8_MMA(1, 1, At, B1); PG8_BAR; PG8_SCHED;
	s_add_i32 s36, s54, s33
	v_lshl_add_u64 v[194:195], v[194:195], 0, s[14:15]
	s_mov_b32 m0, s36
	ds_read_b128 v[186:189], v159 offset:49152
	ds_read_b128 v[190:193], v159 offset:50176
	ds_read_b128 v[198:201], v159 offset:51200
	ds_read_b128 v[202:205], v159 offset:52224
	ds_read_b128 v[206:209], v159 offset:53248
	ds_read_b128 v[210:213], v159 offset:54272
	ds_read_b128 v[214:217], v159 offset:55296
	ds_read_b128 v[218:221], v159 offset:56320
	global_load_lds_dwordx4 v[194:195], off
	s_add_i32 m0, s36, 0x2000
	s_add_u32 s34, s34, 0x40080
	v_lshl_add_u64 v[194:195], v[222:223], 0, s[14:15]
	s_addc_u32 s35, s35, 0
	s_add_i32 s36, s55, s33
	global_load_lds_dwordx4 v[194:195], off
	v_lshl_add_u64 v[194:195], s[34:35], 0, v[130:131]
	s_mov_b32 m0, s36
	s_nop 0
	global_load_lds_dwordx4 v[194:195], off
	v_lshl_add_u64 v[194:195], s[34:35], 0, v[134:135]
	s_add_i32 m0, s36, 0x2000
	s_nop 0
	global_load_lds_dwordx4 v[194:195], off
	v_lshl_add_u64 v[194:195], v[224:225], 0, s[14:15]
	s_mov_b32 m0, s44
	s_nop 0
	global_load_lds_dwordx4 v[194:195], off
	v_lshl_add_u64 v[194:195], v[226:227], 0, s[14:15]
	s_mov_b32 m0, s45
	s_nop 0
	global_load_lds_dwordx4 v[194:195], off
	s_waitcnt vmcnt(8)
	s_waitcnt lgkmcnt(0)
	s_barrier
	s_setprio 1
	s_waitcnt lgkmcnt(0)
	v_mfma_f32_16x16x32_bf16 v[92:95], v[144:147], v[186:189], v[92:95]
	v_mfma_f32_16x16x32_bf16 v[88:91], v[162:165], v[186:189], v[88:91]
	v_mfma_f32_16x16x32_bf16 v[84:87], v[144:147], v[198:201], v[84:87]
	v_mfma_f32_16x16x32_bf16 v[80:83], v[162:165], v[198:201], v[80:83]
	v_mfma_f32_16x16x32_bf16 v[76:79], v[144:147], v[206:209], v[76:79]
	v_mfma_f32_16x16x32_bf16 v[72:75], v[162:165], v[206:209], v[72:75]
	v_mfma_f32_16x16x32_bf16 v[68:71], v[144:147], v[214:217], v[68:71]
	v_mfma_f32_16x16x32_bf16 v[60:63], v[162:165], v[214:217], v[60:63]
	v_mfma_f32_16x16x32_bf16 v[92:95], v[148:151], v[190:193], v[92:95]
	v_mfma_f32_16x16x32_bf16 v[88:91], v[166:169], v[190:193], v[88:91]
	v_mfma_f32_16x16x32_bf16 v[84:87], v[148:151], v[202:205], v[84:87]
	v_mfma_f32_16x16x32_bf16 v[80:83], v[166:169], v[202:205], v[80:83]
	v_mfma_f32_16x16x32_bf16 v[76:79], v[148:151], v[210:213], v[76:79]
	v_mfma_f32_16x16x32_bf16 v[72:75], v[166:169], v[210:213], v[72:75]
	v_mfma_f32_16x16x32_bf16 v[68:71], v[148:151], v[218:221], v[68:71]
	v_mfma_f32_16x16x32_bf16 v[60:63], v[166:169], v[218:221], v[60:63]
	s_setprio 0
	s_setprio 1
	v_mfma_f32_16x16x32_bf16 v[28:31], v[170:173], v[186:189], v[28:31]
	v_mfma_f32_16x16x32_bf16 v[24:27], v[178:181], v[186:189], v[24:27]
	v_mfma_f32_16x16x32_bf16 v[20:23], v[170:173], v[198:201], v[20:23]
	v_mfma_f32_16x16x32_bf16 v[16:19], v[178:181], v[198:201], v[16:19]
	v_mfma_f32_16x16x32_bf16 v[12:15], v[170:173], v[206:209], v[12:15]
	v_mfma_f32_16x16x32_bf16 v[8:11], v[178:181], v[206:209], v[8:11]
	v_mfma_f32_16x16x32_bf16 v[4:7], v[170:173], v[214:217], v[4:7]
	v_mfma_f32_16x16x32_bf16 v[0:3], v[178:181], v[214:217], v[0:3]
	v_mfma_f32_16x16x32_bf16 v[28:31], v[174:177], v[190:193], v[28:31]
	v_mfma_f32_16x16x32_bf16 v[24:27], v[182:185], v[190:193], v[24:27]
	v_mfma_f32_16x16x32_bf16 v[20:23], v[174:177], v[202:205], v[20:23]
	v_mfma_f32_16x16x32_bf16 v[16:19], v[182:185], v[202:205], v[16:19]
	v_mfma_f32_16x16x32_bf16 v[12:15], v[174:177], v[210:213], v[12:15]
	v_mfma_f32_16x16x32_bf16 v[8:11], v[182:185], v[210:213], v[8:11]
	v_mfma_f32_16x16x32_bf16 v[4:7], v[174:177], v[218:221], v[4:7]
	v_mfma_f32_16x16x32_bf16 v[0:3], v[182:185], v[218:221], v[0:3]
	s_setprio 0
	s_add_i32 s53, s53, 2
	s_add_u32 s30, s30, 0x100
	s_addc_u32 s31, s31, 0
	s_add_u32 s51, s51, 0x100
	s_addc_u32 s52, s52, 0
	s_cmp_gt_u32 s53, 13
	s_barrier
	s_cbranch_scc0 .LBB0_525
	s_branch .Lrw1_x

; #define PG8_STAGE(bufoff, gbase, voff) do { _Pragma("unroll") for (int _i = 0; _i < 2; ++_i) \
;         __builtin_amdgcn_global_load_lds((const unsigned*)((const char*)(gbase) + (voff)[_i]), (PG8_LAS unsigned*)(lds + (bufoff) + ldsw + _i * 8192), 16, 0, 0); } while (0)
; #define PG8_LDA(dst, b, h) do { _Pragma("unroll") for (int m = 0; m < 4; ++m) _Pragma("unroll") for (int k = 0; k < 2; ++k) dst[m][k] = *(const PG8_LAS bf16x8*)(lds + PG8_SA(b, h) + aoff + m * 2048 + k * 1024); } while (0)
; #define PG8_LDB(dst, b, h) do { _Pragma("unroll") for (int n = 0; n < 2; ++n) _Pragma("unroll") for (int k = 0; k < 2; ++k) dst[n][k] = *(const PG8_LAS bf16x8*)(lds + PG8_SB(b, h) + boff + n * 2048 + k * 1024); } while (0)
; #define PG8_MMA(ai, bj, At, Bt) do { __builtin_amdgcn_s_setprio(1); _Pragma("unroll") for (int m = 0; m < 4; ++m) _Pragma("unroll") for (int n = 0; n < 2; ++n) _Pragma("unroll") for (int k = 0; k < 2; ++k) \
;         acc[ai][bj][m][n] = __builtin_amdgcn_mfma_f32_16x16x32_bf16(Bt[n][k], At[m][k], acc[ai][bj][m][n], 0, 0, 0); __builtin_amdgcn_s_setprio(0); } while (0)
; #define PG8_WAIT_V(n) asm volatile("s_waitcnt vmcnt(" #n ")" ::: "memory")
; #define PG8_WAIT_L(n) asm volatile("s_waitcnt lgkmcnt(" #n ")" ::: "memory")
; #define PG8_BAR __builtin_amdgcn_s_barrier()
; #define PG8_SCHED __builtin_amdgcn_sched_barrier(0)
; template <class Epi, class Sched, bool ALIGN_EPI = false, bool SP2 = false>
; __device__ __forceinline__ void gemm_phase(PG8_LAS unsigned char* lds, const Gemm g, const Sched& S, const Epi& E) {
;     ...
;             PG8_WAIT_V(8); PG8_WAIT_L(0); PG8_BAR; PG8_MMA(1, 0, At, B0); PG8_MMA(1, 1, At, B1); PG8_BAR; PG8_SCHED;
;             PG8_LDB(B0, 1, 0); PG8_LDB(B1, 1, 1); PG8_SCHED; PG8_LDA(At, 1, 0); PG8_STAGE(PG8_SA(0, 1), a2 + hstep, voffA);
;             PG8_WAIT_V(8); PG8_WAIT_L(0); PG8_BAR; PG8_MMA(0, 0, At, B0); PG8_MMA(0, 1, At, B1); PG8_BAR; PG8_SCHED;
.Lrw2_b1:
	s_waitcnt lgkmcnt(0)
	s_barrier
	s_setprio 1
	s_waitcnt lgkmcnt(0)
	v_mfma_f32_16x16x32_bf16 v[60:63], v[144:147], v[184:187], v[60:63]
	v_mfma_f32_16x16x32_bf16 v[52:55], v[160:163], v[184:187], v[52:55]
	v_mfma_f32_16x16x32_bf16 v[44:47], v[144:147], v[192:195], v[44:47]
	v_mfma_f32_16x16x32_bf16 v[36:39], v[160:163], v[192:195], v[36:39]
	v_mfma_f32_16x16x32_bf16 v[28:31], v[144:147], v[202:205], v[28:31]
	v_mfma_f32_16x16x32_bf16 v[20:23], v[160:163], v[202:205], v[20:23]
	v_mfma_f32_16x16x32_bf16 v[12:15], v[144:147], v[210:213], v[12:15]
	v_mfma_f32_16x16x32_bf16 v[4:7], v[160:163], v[210:213], v[4:7]
	v_mfma_f32_16x16x32_bf16 v[60:63], v[156:159], v[188:191], v[60:63]
	v_mfma_f32_16x16x32_bf16 v[52:55], v[164:167], v[188:191], v[52:55]
	v_mfma_f32_16x16x32_bf16 v[44:47], v[156:159], v[198:201], v[44:47]
	v_mfma_f32_16x16x32_bf16 v[36:39], v[164:167], v[198:201], v[36:39]
	v_mfma_f32_16x16x32_bf16 v[28:31], v[156:159], v[206:209], v[28:31]
	v_mfma_f32_16x16x32_bf16 v[20:23], v[164:167], v[206:209], v[20:23]
	v_mfma_f32_16x16x32_bf16 v[12:15], v[156:159], v[214:217], v[12:15]
	v_mfma_f32_16x16x32_bf16 v[4:7], v[164:167], v[214:217], v[4:7]
	s_setprio 0
	s_setprio 1
	v_mfma_f32_16x16x32_bf16 v[56:59], v[168:171], v[184:187], v[56:59]
	v_mfma_f32_16x16x32_bf16 v[48:51], v[176:179], v[184:187], v[48:51]
	v_mfma_f32_16x16x32_bf16 v[40:43], v[168:171], v[192:195], v[40:43]
	v_mfma_f32_16x16x32_bf16 v[32:35], v[176:179], v[192:195], v[32:35]
	v_mfma_f32_16x16x32_bf16 v[24:27], v[168:171], v[202:205], v[24:27]
	v_mfma_f32_16x16x32_bf16 v[16:19], v[176:179], v[202:205], v[16:19]
	v_mfma_f32_16x16x32_bf16 v[8:11], v[168:171], v[210:213], v[8:11]
	v_mfma_f32_16x16x32_bf16 v[0:3], v[176:179], v[210:213], v[0:3]
	v_mfma_f32_16x16x32_bf16 v[56:59], v[172:175], v[188:191], v[56:59]
	v_mfma_f32_16x16x32_bf16 v[48:51], v[180:183], v[188:191], v[48:51]
	v_mfma_f32_16x16x32_bf16 v[40:43], v[172:175], v[198:201], v[40:43]
	v_mfma_f32_16x16x32_bf16 v[32:35], v[180:183], v[198:201], v[32:35]
	v_mfma_f32_16x16x32_bf16 v[24:27], v[172:175], v[206:209], v[24:27]
	v_mfma_f32_16x16x32_bf16 v[16:19], v[180:183], v[206:209], v[16:19]
	v_mfma_f32_16x16x32_bf16 v[8:11], v[172:175], v[214:217], v[8:11]
	v_mfma_f32_16x16x32_bf16 v[0:3], v[180:183], v[214:217], v[0:3]
	s_setprio 0
	s_barrier
	s_add_i32 s51, 0, 0x18000
	v_add_u32_e32 v148, s51, v151
	s_add_i32 s52, 0, 0x1c000
	ds_read_b128 v[144:147], v148
	ds_read_b128 v[156:159], v148 offset:1024
	ds_read_b128 v[160:163], v148 offset:2048
	ds_read_b128 v[164:167], v148 offset:3072
	v_add_u32_e32 v148, s52, v151
	ds_read_b128 v[168:171], v148
	ds_read_b128 v[172:175], v148 offset:1024
	ds_read_b128 v[176:179], v148 offset:2048
	ds_read_b128 v[180:183], v148 offset:3072
	s_add_u32 s30, s30, 0x40000
	s_addc_u32 s31, s31, 0
	s_mov_b32 m0, s35
	v_lshl_add_u64 v[226:227], s[30:31], 0, v[128:129]
	ds_read_b128 v[184:187], v155 offset:32768
	ds_read_b128 v[188:191], v155 offset:33792
	ds_read_b128 v[192:195], v155 offset:34816
	ds_read_b128 v[198:201], v155 offset:35840
	ds_read_b128 v[202:205], v155 offset:36864
	ds_read_b128 v[206:209], v155 offset:37888
	ds_read_b128 v[210:213], v155 offset:38912
	ds_read_b128 v[214:217], v155 offset:39936
	global_load_lds_dwordx4 v[226:227], off
	v_lshl_add_u64 v[226:227], s[30:31], 0, v[132:133]
	s_mov_b32 m0, s36
	s_nop 0
	global_load_lds_dwordx4 v[226:227], off
	s_waitcnt vmcnt(8)
	s_waitcnt lgkmcnt(0)
	s_barrier
	s_setprio 1
	s_waitcnt lgkmcnt(0)
	v_mfma_f32_16x16x32_bf16 v[124:127], v[144:147], v[184:187], v[124:127]
	v_mfma_f32_16x16x32_bf16 v[116:119], v[160:163], v[184:187], v[116:119]
	v_mfma_f32_16x16x32_bf16 v[108:111], v[144:147], v[192:195], v[108:111]
	v_mfma_f32_16x16x32_bf16 v[100:103], v[160:163], v[192:195], v[100:103]
	v_mfma_f32_16x16x32_bf16 v[92:95], v[144:147], v[202:205], v[92:95]
	v_mfma_f32_16x16x32_bf16 v[84:87], v[160:163], v[202:205], v[84:87]
	v_mfma_f32_16x16x32_bf16 v[76:79], v[144:147], v[210:213], v[76:79]
	v_mfma_f32_16x16x32_bf16 v[68:71], v[160:163], v[210:213], v[68:71]
	v_mfma_f32_16x16x32_bf16 v[124:127], v[156:159], v[188:191], v[124:127]
	v_mfma_f32_16x16x32_bf16 v[116:119], v[164:167], v[188:191], v[116:119]
	v_mfma_f32_16x16x32_bf16 v[108:111], v[156:159], v[198:201], v[108:111]
	v_mfma_f32_16x16x32_bf16 v[100:103], v[164:167], v[198:201], v[100:103]
	v_mfma_f32_16x16x32_bf16 v[92:95], v[156:159], v[206:209], v[92:95]
	v_mfma_f32_16x16x32_bf16 v[84:87], v[164:167], v[206:209], v[84:87]
	v_mfma_f32_16x16x32_bf16 v[76:79], v[156:159], v[214:217], v[76:79]
	v_mfma_f32_16x16x32_bf16 v[68:71], v[164:167], v[214:217], v[68:71]
	s_setprio 0
	s_setprio 1
	v_mfma_f32_16x16x32_bf16 v[120:123], v[168:171], v[184:187], v[120:123]
	v_mfma_f32_16x16x32_bf16 v[112:115], v[176:179], v[184:187], v[112:115]
	v_mfma_f32_16x16x32_bf16 v[104:107], v[168:171], v[192:195], v[104:107]
	v_mfma_f32_16x16x32_bf16 v[96:99], v[176:179], v[192:195], v[96:99]
	v_mfma_f32_16x16x32_bf16 v[88:91], v[168:171], v[202:205], v[88:91]
	v_mfma_f32_16x16x32_bf16 v[80:83], v[176:179], v[202:205], v[80:83]
	v_mfma_f32_16x16x32_bf16 v[72:75], v[168:171], v[210:213], v[72:75]
	v_mfma_f32_16x16x32_bf16 v[64:67], v[176:179], v[210:213], v[64:67]
	v_mfma_f32_16x16x32_bf16 v[120:123], v[172:175], v[188:191], v[120:123]
	v_mfma_f32_16x16x32_bf16 v[112:115], v[180:183], v[188:191], v[112:115]
	v_mfma_f32_16x16x32_bf16 v[104:107], v[172:175], v[198:201], v[104:107]
	v_mfma_f32_16x16x32_bf16 v[96:99], v[180:183], v[198:201], v[96:99]
	v_mfma_f32_16x16x32_bf16 v[88:91], v[172:175], v[206:209], v[88:91]
	v_mfma_f32_16x16x32_bf16 v[80:83], v[180:183], v[206:209], v[80:83]
	v_mfma_f32_16x16x32_bf16 v[72:75], v[172:175], v[214:217], v[72:75]
	v_mfma_f32_16x16x32_bf16 v[64:67], v[180:183], v[214:217], v[64:67]
	s_setprio 0
	s_barrier
; #define PG8_STAGE(bufoff, gbase, voff) do { _Pragma("unroll") for (int _i = 0; _i < 2; ++_i) \
;         __builtin_amdgcn_global_load_lds((const unsigned*)((const char*)(gbase) + (voff)[_i]), (PG8_LAS unsigned*)(lds + (bufoff) + ldsw + _i * 8192), 16, 0, 0); } while (0)
; #define PG8_LDA(dst, b, h) do { _Pragma("unroll") for (int m = 0; m < 4; ++m) _Pragma("unroll") for (int k = 0; k < 2; ++k) dst[m][k] = *(const PG8_LAS bf16x8*)(lds + PG8_SA(b, h) + aoff + m * 2048 + k * 1024); } while (0)
; #define PG8_MMA(ai, bj, At, Bt) do { __builtin_amdgcn_s_setprio(1); _Pragma("unroll") for (int m = 0; m < 4; ++m) _Pragma("unroll") for (int n = 0; n < 2; ++n) _Pragma("unroll") for (int k = 0; k < 2; ++k) \
;         acc[ai][bj][m][n] = __builtin_amdgcn_mfma_f32_16x16x32_bf16(Bt[n][k], At[m][k], acc[ai][bj][m][n], 0, 0, 0); __builtin_amdgcn_s_setprio(0); } while (0)
; #define PG8_WAIT_V(n) asm volatile("s_waitcnt vmcnt(" #n ")" ::: "memory")
; #define PG8_WAIT_L(n) asm volatile("s_waitcnt lgkmcnt(" #n ")" ::: "memory")
; #define PG8_BAR __builtin_amdgcn_s_barrier()
; #define PG8_SCHED __builtin_amdgcn_sched_barrier(0)
; template <class Epi, class Sched, bool ALIGN_EPI = false, bool SP2 = false>
; __device__ __forceinline__ void gemm_phase(PG8_LAS unsigned char* lds, const Gemm g, const Sched& S, const Epi& E) {
;     ...
;             PG8_LDA(At, 1, 1); PG8_STAGE(PG8_SB(1, 0), b3, voffB); PG8_STAGE(PG8_SB(1, 1), b3 + hstep, voffB); PG8_STAGE(PG8_SA(1, 0), a3, voffA);
;             PG8_WAIT_V(8); PG8_WAIT_L(0); PG8_BAR; PG8_MMA(1, 0, At, B0); PG8_MMA(1, 1, At, B1); PG8_BAR; PG8_SCHED;
	s_add_i32 s30, s51, s33
	v_lshl_add_u64 v[218:219], v[218:219], 0, s[12:13]
	s_mov_b32 m0, s30
	ds_read_b128 v[184:187], v155 offset:49152
	ds_read_b128 v[188:191], v155 offset:50176
	ds_read_b128 v[192:195], v155 offset:51200
	ds_read_b128 v[198:201], v155 offset:52224
	ds_read_b128 v[202:205], v155 offset:53248
	ds_read_b128 v[206:209], v155 offset:54272
	ds_read_b128 v[210:213], v155 offset:55296
	ds_read_b128 v[214:217], v155 offset:56320
	global_load_lds_dwordx4 v[218:219], off
	s_add_i32 m0, s30, 0x2000
	s_add_u32 s28, s28, 0x40080
	v_lshl_add_u64 v[218:219], v[220:221], 0, s[12:13]
	s_addc_u32 s29, s29, 0
	s_add_i32 s30, s52, s33
	global_load_lds_dwordx4 v[218:219], off
	v_lshl_add_u64 v[218:219], s[28:29], 0, v[130:131]
	s_mov_b32 m0, s30
	s_nop 0
	global_load_lds_dwordx4 v[218:219], off
	v_lshl_add_u64 v[218:219], s[28:29], 0, v[134:135]
	s_add_i32 m0, s30, 0x2000
	s_nop 0
	global_load_lds_dwordx4 v[218:219], off
	v_lshl_add_u64 v[218:219], v[222:223], 0, s[12:13]
	s_mov_b32 m0, s40
	s_nop 0
	global_load_lds_dwordx4 v[218:219], off
	v_lshl_add_u64 v[218:219], v[224:225], 0, s[12:13]
	s_mov_b32 m0, s41
	s_nop 0
	global_load_lds_dwordx4 v[218:219], off
	s_waitcnt vmcnt(8)
	s_waitcnt lgkmcnt(0)
	s_barrier
	s_setprio 1
	s_waitcnt lgkmcnt(0)
	v_mfma_f32_16x16x32_bf16 v[60:63], v[144:147], v[184:187], v[60:63]
	v_mfma_f32_16x16x32_bf16 v[52:55], v[160:163], v[184:187], v[52:55]
	v_mfma_f32_16x16x32_bf16 v[44:47], v[144:147], v[192:195], v[44:47]
	v_mfma_f32_16x16x32_bf16 v[36:39], v[160:163], v[192:195], v[36:39]
	v_mfma_f32_16x16x32_bf16 v[28:31], v[144:147], v[202:205], v[28:31]
	v_mfma_f32_16x16x32_bf16 v[20:23], v[160:163], v[202:205], v[20:23]
	v_mfma_f32_16x16x32_bf16 v[12:15], v[144:147], v[210:213], v[12:15]
	v_mfma_f32_16x16x32_bf16 v[4:7], v[160:163], v[210:213], v[4:7]
	v_mfma_f32_16x16x32_bf16 v[60:63], v[156:159], v[188:191], v[60:63]
	v_mfma_f32_16x16x32_bf16 v[52:55], v[164:167], v[188:191], v[52:55]
	v_mfma_f32_16x16x32_bf16 v[44:47], v[156:159], v[198:201], v[44:47]
	v_mfma_f32_16x16x32_bf16 v[36:39], v[164:167], v[198:201], v[36:39]
	v_mfma_f32_16x16x32_bf16 v[28:31], v[156:159], v[206:209], v[28:31]
	v_mfma_f32_16x16x32_bf16 v[20:23], v[164:167], v[206:209], v[20:23]
	v_mfma_f32_16x16x32_bf16 v[12:15], v[156:159], v[214:217], v[12:15]
	v_mfma_f32_16x16x32_bf16 v[4:7], v[164:167], v[214:217], v[4:7]
	s_setprio 0
	s_setprio 1
	v_mfma_f32_16x16x32_bf16 v[56:59], v[168:171], v[184:187], v[56:59]
	v_mfma_f32_16x16x32_bf16 v[48:51], v[176:179], v[184:187], v[48:51]
	v_mfma_f32_16x16x32_bf16 v[40:43], v[168:171], v[192:195], v[40:43]
	v_mfma_f32_16x16x32_bf16 v[32:35], v[176:179], v[192:195], v[32:35]
	v_mfma_f32_16x16x32_bf16 v[24:27], v[168:171], v[202:205], v[24:27]
	v_mfma_f32_16x16x32_bf16 v[16:19], v[176:179], v[202:205], v[16:19]
	v_mfma_f32_16x16x32_bf16 v[8:11], v[168:171], v[210:213], v[8:11]
	v_mfma_f32_16x16x32_bf16 v[0:3], v[176:179], v[210:213], v[0:3]
	v_mfma_f32_16x16x32_bf16 v[56:59], v[172:175], v[188:191], v[56:59]
	v_mfma_f32_16x16x32_bf16 v[48:51], v[180:183], v[188:191], v[48:51]
	v_mfma_f32_16x16x32_bf16 v[40:43], v[172:175], v[198:201], v[40:43]
	v_mfma_f32_16x16x32_bf16 v[32:35], v[180:183], v[198:201], v[32:35]
	v_mfma_f32_16x16x32_bf16 v[24:27], v[172:175], v[206:209], v[24:27]
	v_mfma_f32_16x16x32_bf16 v[16:19], v[180:183], v[206:209], v[16:19]
	v_mfma_f32_16x16x32_bf16 v[8:11], v[172:175], v[214:217], v[8:11]
	v_mfma_f32_16x16x32_bf16 v[0:3], v[180:183], v[214:217], v[0:3]
	s_setprio 0
	s_add_i32 s50, s50, 2
	s_add_u32 s26, s26, 0x100
	s_addc_u32 s27, s27, 0
	s_add_u32 s48, s48, 0x100
	s_addc_u32 s49, s49, 0
	s_cmp_gt_u32 s50, 13
	s_barrier
	s_cbranch_scc0 .LBB0_1146
	s_branch .Lrw2_x
